# GLA pass-1 item: k*exp(-c) instead of the f32 division expansion; log-sigmoid loop interleaved two tokens at a time with dead log branches removed
# speedup vs baseline: 1.0508x; 1.0027x over previous
.LBB0_189:
	s_or_b64 exec, exec, s[0:1]
	v_ashrrev_i32_e32 v55, 6, v33
	v_lshlrev_b32_e32 v28, 3, v55
	v_cmp_eq_u32_e64 s[40:41], 0, v13
	v_sub_u32_e32 v0, 31, v28
	v_lshlrev_b32_e32 v8, 6, v10
	v_cndmask_b32_e64 v29, v0, v28, s[40:41]
	v_ashrrev_i32_e32 v9, 31, v8
	v_add_u32_e32 v0, v29, v32
	v_mov_b64_e32 v[4:5], s[60:61]
	s_movk_i32 s2, 0x3700
	v_and_b32_e32 v54, 63, v33
	v_mad_i64_i32 v[0:1], s[0:1], v0, s2, v[4:5]
	v_lshlrev_b64 v[2:3], 1, v[8:9]
	v_lshl_add_u64 v[0:1], v[0:1], 0, v[2:3]
	v_lshlrev_b32_e32 v152, 1, v54
	v_lshl_add_u64 v[0:1], v[0:1], 0, v[152:153]
	v_or_b32_e32 v27, 1, v28
	global_load_ushort v30, v[0:1], off
	global_load_ushort v31, v[0:1], off offset:512
	v_sub_u32_e32 v0, 31, v27
	v_cndmask_b32_e64 v26, v0, v27, s[40:41]
	v_add_u32_e32 v0, v26, v32
	v_mad_i64_i32 v[0:1], s[0:1], v0, s2, v[4:5]
	v_lshl_add_u64 v[0:1], v[0:1], 0, v[2:3]
	v_lshl_add_u64 v[0:1], v[0:1], 0, v[152:153]
	v_or_b32_e32 v25, 2, v28
	global_load_ushort v34, v[0:1], off
	global_load_ushort v35, v[0:1], off offset:512
	v_sub_u32_e32 v0, 31, v25
	v_cndmask_b32_e64 v24, v0, v25, s[40:41]
	v_add_u32_e32 v0, v24, v32
	v_mad_i64_i32 v[0:1], s[0:1], v0, s2, v[4:5]
	v_lshl_add_u64 v[0:1], v[0:1], 0, v[2:3]
	v_lshl_add_u64 v[0:1], v[0:1], 0, v[152:153]
	v_or_b32_e32 v23, 3, v28
	global_load_ushort v36, v[0:1], off
	global_load_ushort v37, v[0:1], off offset:512
	v_sub_u32_e32 v0, 31, v23
	v_cndmask_b32_e64 v22, v0, v23, s[40:41]
	v_add_u32_e32 v0, v22, v32
	v_mad_i64_i32 v[0:1], s[0:1], v0, s2, v[4:5]
	v_lshl_add_u64 v[0:1], v[0:1], 0, v[2:3]
	v_lshl_add_u64 v[0:1], v[0:1], 0, v[152:153]
	v_or_b32_e32 v21, 4, v28
	global_load_ushort v38, v[0:1], off
	global_load_ushort v39, v[0:1], off offset:512
	v_sub_u32_e32 v0, 31, v21
	v_cndmask_b32_e64 v20, v0, v21, s[40:41]
	v_add_u32_e32 v0, v20, v32
	v_mad_i64_i32 v[0:1], s[0:1], v0, s2, v[4:5]
	v_lshl_add_u64 v[0:1], v[0:1], 0, v[2:3]
	v_lshl_add_u64 v[0:1], v[0:1], 0, v[152:153]
	v_or_b32_e32 v19, 5, v28
	global_load_ushort v40, v[0:1], off
	global_load_ushort v41, v[0:1], off offset:512
	v_sub_u32_e32 v0, 31, v19
	v_cndmask_b32_e64 v18, v0, v19, s[40:41]
	v_add_u32_e32 v0, v18, v32
	v_mad_i64_i32 v[0:1], s[0:1], v0, s2, v[4:5]
	v_lshl_add_u64 v[0:1], v[0:1], 0, v[2:3]
	v_lshl_add_u64 v[0:1], v[0:1], 0, v[152:153]
	v_or_b32_e32 v17, 6, v28
	global_load_ushort v42, v[0:1], off
	global_load_ushort v43, v[0:1], off offset:512
	v_sub_u32_e32 v0, 31, v17
	v_cndmask_b32_e64 v16, v0, v17, s[40:41]
	v_add_u32_e32 v0, v16, v32
	v_mad_i64_i32 v[0:1], s[0:1], v0, s2, v[4:5]
	v_lshl_add_u64 v[0:1], v[0:1], 0, v[2:3]
	v_lshl_add_u64 v[0:1], v[0:1], 0, v[152:153]
	v_or_b32_e32 v15, 7, v28
	global_load_ushort v44, v[0:1], off
	global_load_ushort v45, v[0:1], off offset:512
	v_sub_u32_e32 v0, 31, v15
	v_cndmask_b32_e64 v14, v0, v15, s[40:41]
	v_add_u32_e32 v0, v14, v32
	v_mad_i64_i32 v[0:1], s[0:1], v0, s2, v[4:5]
	v_lshl_add_u64 v[0:1], v[0:1], 0, v[2:3]
	v_lshl_add_u64 v[0:1], v[0:1], 0, v[152:153]
	global_load_ushort v46, v[0:1], off
	global_load_ushort v47, v[0:1], off offset:512
	v_add_u32_e32 v0, 0x100, v33
	v_ashrrev_i32_e32 v51, 4, v33
	v_ashrrev_i32_e32 v50, 4, v0
	v_sub_u32_e32 v0, 31, v51
	v_sub_u32_e32 v53, 31, v50
	v_cndmask_b32_e64 v0, v0, v51, s[40:41]
	v_lshlrev_b32_e32 v48, 7, v10
	v_cndmask_b32_e64 v53, v53, v50, s[40:41]
	v_add_u32_e32 v0, v0, v32
	v_ashrrev_i32_e32 v49, 31, v48
	v_lshlrev_b32_e32 v56, 3, v33
	v_add_u32_e32 v53, v53, v32
	v_mad_i64_i32 v[0:1], s[0:1], v0, s2, v[4:5]
	v_lshlrev_b64 v[6:7], 1, v[48:49]
	v_and_b32_e32 v52, 0x78, v56
	v_mad_i64_i32 v[4:5], s[0:1], v53, s2, v[4:5]
	v_lshl_add_u64 v[0:1], v[0:1], 0, v[6:7]
	v_lshlrev_b32_e32 v152, 1, v52
	v_lshl_add_u64 v[4:5], v[4:5], 0, v[6:7]
	v_readlane_b32 s2, v249, 1
	v_lshl_add_u64 v[0:1], v[0:1], 0, v[152:153]
	v_lshl_add_u64 v[4:5], v[4:5], 0, v[152:153]
	v_cndmask_b32_e64 v152, v187, v188, s[40:41]
	v_readlane_b32 s3, v249, 2
	v_readlane_b32 s0, v247, 51
	v_readlane_b32 s1, v247, 52
	s_cmp_lg_u64 s[40:41], 0
	s_movk_i32 s101, 0x80
	s_cselect_b32 s100, 0x70, s101
	s_load_dwordx2 s[100:101], s[2:3], s100
	v_lshlrev_b32_e32 v152, 2, v54
	global_load_dwordx4 v[0:3], v[0:1], off offset:1024
	s_mov_b32 s8, 0x7f800000
	global_load_dwordx4 v[4:7], v[4:5], off offset:1024
	v_mul_u32_u24_e32 v52, 40, v52
	v_lshlrev_b32_e32 v52, 1, v52
	v_lshl_add_u32 v51, v51, 1, v52
	s_waitcnt lgkmcnt(0)
	v_mov_b32_e32 v58, s100
	v_mov_b32_e32 v59, s101
	v_lshl_add_u64 v[58:59], v[58:59], 0, s[0:1]
	v_lshl_add_u64 v[58:59], v[8:9], 2, v[58:59]
	v_lshl_add_u64 v[72:73], v[58:59], 0, v[152:153]
	s_movk_i32 s0, 0x1000
	v_add_co_u32_e32 v58, vcc, s0, v72
	s_movk_i32 s0, 0x2000
	s_nop 0
	v_addc_co_u32_e32 v59, vcc, 0, v73, vcc
	v_add_co_u32_e32 v74, vcc, s0, v72
	s_movk_i32 s0, 0x3000
	s_nop 0
	v_addc_co_u32_e32 v75, vcc, 0, v73, vcc
	global_load_dword v67, v[72:73], off
	global_load_dword v70, v[72:73], off offset:1024
	global_load_dword v68, v[72:73], off offset:2048
	global_load_dword v69, v[72:73], off offset:3072
	v_add_co_u32_e32 v72, vcc, s0, v72
	global_load_dword v63, v[74:75], off offset:-4096
	global_load_dword v66, v[58:59], off offset:1024
	global_load_dword v64, v[58:59], off offset:2048
	global_load_dword v65, v[58:59], off offset:3072
	s_nop 0
	global_load_dword v59, v[74:75], off
	global_load_dword v62, v[74:75], off offset:1024
	global_load_dword v60, v[74:75], off offset:2048
	global_load_dword v61, v[74:75], off offset:3072
	v_addc_co_u32_e32 v73, vcc, 0, v73, vcc
	global_load_dword v53, v[72:73], off
	global_load_dword v58, v[72:73], off offset:1024
	global_load_dword v57, v[72:73], off offset:2048
	global_load_dword v9, v[72:73], off offset:3072
	s_cmp_lg_u64 s[40:41], 0
	s_movk_i32 s101, 0x88
	s_cselect_b32 s100, 0x78, s101
	s_load_dwordx2 s[100:101], s[2:3], s100
	v_readlane_b32 s0, v247, 53
	s_mov_b32 s2, 0xbfb8aa3b
	s_mov_b32 s1, 0x800000
	v_add_u32_e32 v8, s0, v8
	v_or_b32_e32 v74, v54, v8
	v_ashrrev_i32_e32 v75, 31, v74
	v_lshlrev_b32_e32 v8, 9, v55
	s_mov_b32 s3, 0x3f317217
	s_mov_b32 s0, 0x3d800000
	s_waitcnt lgkmcnt(0)
	v_mov_b32_e32 v72, s100
	v_mov_b32_e32 v73, s101
	v_lshl_add_u64 v[72:73], v[74:75], 2, v[72:73]
	global_load_dword v72, v[72:73], off
	v_cmp_gt_u32_e32 vcc, 0x80, v167
	s_waitcnt vmcnt(0)
	s_and_saveexec_b64 s[100:101], vcc
	v_lshlrev_b32_e32 v236, 16, v242
	v_and_b32_e32 v237, 0xffff0000, v242
	v_lshlrev_b32_e32 v238, 16, v243
	v_and_b32_e32 v239, 0xffff0000, v243
	ds_write_b128 v244, v[236:239] offset:23552
	s_or_b64 exec, exec, s[100:101]
	s_waitcnt lgkmcnt(0)
	s_barrier
	s_waitcnt vmcnt(0)
	ds_read_b128 v[90:93], v8 offset:23552
	ds_read_b128 v[94:97], v8 offset:23568
	ds_read_b128 v[98:101], v8 offset:23584
	ds_read_b128 v[102:105], v8 offset:23600
	ds_read_b128 v[106:109], v8 offset:23616
	ds_read_b128 v[110:113], v8 offset:23632
	ds_read_b128 v[114:117], v8 offset:23648
	ds_read_b128 v[118:121], v8 offset:23664
	ds_read_b128 v[122:125], v8 offset:23680
	ds_read_b128 v[126:129], v8 offset:23696
	ds_read_b128 v[130:133], v8 offset:23712
	ds_read_b128 v[134:137], v8 offset:23728
	s_waitcnt lgkmcnt(4)
	v_mul_f32_e32 v138, v70, v91
	v_mul_f32_e32 v141, v70, v107
	v_fmac_f32_e32 v138, v67, v90
	v_fmac_f32_e32 v141, v67, v106
	v_fmac_f32_e32 v138, v68, v92
	v_fmac_f32_e32 v141, v68, v108
	v_fmac_f32_e32 v138, v69, v93
	v_fmac_f32_e32 v141, v69, v109
	v_mul_f32_e32 v139, v66, v95
	v_mul_f32_e32 v142, v66, v111
	v_fmac_f32_e32 v139, v63, v94
	v_fmac_f32_e32 v142, v63, v110
	v_fmac_f32_e32 v139, v64, v96
	v_fmac_f32_e32 v142, v64, v112
	v_fmac_f32_e32 v139, v65, v97
	v_fmac_f32_e32 v142, v65, v113
	v_add_f32_e32 v138, v72, v138
	v_add_f32_e32 v141, v72, v141
	v_add_f32_e32 v138, v138, v139
	v_add_f32_e32 v141, v141, v142
	v_mul_f32_e32 v139, v62, v99
	v_mul_f32_e32 v142, v62, v115
	v_fmac_f32_e32 v139, v59, v98
	v_fmac_f32_e32 v142, v59, v114
	v_fmac_f32_e32 v139, v60, v100
	v_fmac_f32_e32 v142, v60, v116
	v_fmac_f32_e32 v139, v61, v101
	v_fmac_f32_e32 v142, v61, v117
	v_add_f32_e32 v138, v138, v139
	v_add_f32_e32 v141, v141, v142
	v_mul_f32_e32 v139, v58, v103
	v_mul_f32_e32 v142, v58, v119
	v_fmac_f32_e32 v139, v53, v102
	v_fmac_f32_e32 v142, v53, v118
	v_fmac_f32_e32 v139, v57, v104
	v_fmac_f32_e32 v142, v57, v120
	v_fmac_f32_e32 v139, v9, v105
	v_fmac_f32_e32 v142, v9, v121
	v_add_f32_e32 v138, v138, v139
	v_add_f32_e32 v141, v141, v142
	ds_read_b128 v[90:93], v8 offset:23744
	ds_read_b128 v[94:97], v8 offset:23760
	ds_read_b128 v[98:101], v8 offset:23776
	ds_read_b128 v[102:105], v8 offset:23792
	ds_read_b128 v[106:109], v8 offset:23808
	ds_read_b128 v[110:113], v8 offset:23824
	ds_read_b128 v[114:117], v8 offset:23840
	ds_read_b128 v[118:121], v8 offset:23856
	v_min_f32_e32 v140, 0, v138
	v_min_f32_e32 v143, 0, v141
	v_mul_f32_e64 v138, |v138|, s2
	v_mul_f32_e64 v141, |v141|, s2
	v_exp_f32_e32 v138, v138
	v_exp_f32_e32 v141, v141
	v_add_f32_e32 v138, 1.0, v138
	v_add_f32_e32 v141, 1.0, v141
	v_log_f32_e32 v138, v138
	v_log_f32_e32 v141, v141
	v_mul_f32_e32 v139, 0x3f317217, v138
	v_mul_f32_e32 v142, 0x3f317217, v141
	v_fma_f32 v139, v138, s3, -v139
	v_fma_f32 v142, v141, s3, -v142
	v_fmac_f32_e32 v139, 0x3377d1cf, v138
	v_fmac_f32_e32 v142, 0x3377d1cf, v141
	v_fmac_f32_e32 v139, 0x3f317217, v138
	v_fmac_f32_e32 v142, 0x3f317217, v141
	v_sub_f32_e32 v138, v140, v139
	v_sub_f32_e32 v141, v143, v142
	v_fma_f32 v71, v138, s0, 0
	v_fmamk_f32 v73, v141, 0x3d800000, v71
	s_waitcnt lgkmcnt(4)
	v_mul_f32_e32 v138, v70, v123
	v_mul_f32_e32 v141, v70, v91
	v_fmac_f32_e32 v138, v67, v122
	v_fmac_f32_e32 v141, v67, v90
	v_fmac_f32_e32 v138, v68, v124
	v_fmac_f32_e32 v141, v68, v92
	v_fmac_f32_e32 v138, v69, v125
	v_fmac_f32_e32 v141, v69, v93
	v_mul_f32_e32 v139, v66, v127
	v_mul_f32_e32 v142, v66, v95
	v_fmac_f32_e32 v139, v63, v126
	v_fmac_f32_e32 v142, v63, v94
	v_fmac_f32_e32 v139, v64, v128
	v_fmac_f32_e32 v142, v64, v96
	v_fmac_f32_e32 v139, v65, v129
	v_fmac_f32_e32 v142, v65, v97
	v_add_f32_e32 v138, v72, v138
	v_add_f32_e32 v141, v72, v141
	v_add_f32_e32 v138, v138, v139
	v_add_f32_e32 v141, v141, v142
	v_mul_f32_e32 v139, v62, v131
	v_mul_f32_e32 v142, v62, v99
	v_fmac_f32_e32 v139, v59, v130
	v_fmac_f32_e32 v142, v59, v98
	v_fmac_f32_e32 v139, v60, v132
	v_fmac_f32_e32 v142, v60, v100
	v_fmac_f32_e32 v139, v61, v133
	v_fmac_f32_e32 v142, v61, v101
	v_add_f32_e32 v138, v138, v139
	v_add_f32_e32 v141, v141, v142
	v_mul_f32_e32 v139, v58, v135
	v_mul_f32_e32 v142, v58, v103
	v_fmac_f32_e32 v139, v53, v134
	v_fmac_f32_e32 v142, v53, v102
	v_fmac_f32_e32 v139, v57, v136
	v_fmac_f32_e32 v142, v57, v104
	v_fmac_f32_e32 v139, v9, v137
	v_fmac_f32_e32 v142, v9, v105
	v_add_f32_e32 v138, v138, v139
	v_add_f32_e32 v141, v141, v142
	ds_read_b128 v[122:125], v8 offset:23872
	ds_read_b128 v[126:129], v8 offset:23888
	ds_read_b128 v[130:133], v8 offset:23904
	ds_read_b128 v[134:137], v8 offset:23920
	ds_read_b128 v[90:93], v8 offset:23936
	ds_read_b128 v[94:97], v8 offset:23952
	ds_read_b128 v[98:101], v8 offset:23968
	ds_read_b128 v[102:105], v8 offset:23984
	v_min_f32_e32 v140, 0, v138
	v_min_f32_e32 v143, 0, v141
	v_mul_f32_e64 v138, |v138|, s2
	v_mul_f32_e64 v141, |v141|, s2
	v_exp_f32_e32 v138, v138
	v_exp_f32_e32 v141, v141
	v_add_f32_e32 v138, 1.0, v138
	v_add_f32_e32 v141, 1.0, v141
	v_log_f32_e32 v138, v138
	v_log_f32_e32 v141, v141
	v_mul_f32_e32 v139, 0x3f317217, v138
	v_mul_f32_e32 v142, 0x3f317217, v141
	v_fma_f32 v139, v138, s3, -v139
	v_fma_f32 v142, v141, s3, -v142
	v_fmac_f32_e32 v139, 0x3377d1cf, v138
	v_fmac_f32_e32 v142, 0x3377d1cf, v141
	v_fmac_f32_e32 v139, 0x3f317217, v138
	v_fmac_f32_e32 v142, 0x3f317217, v141
	v_sub_f32_e32 v138, v140, v139
	v_sub_f32_e32 v141, v143, v142
	v_fmamk_f32 v74, v138, 0x3d800000, v73
	v_fmamk_f32 v75, v141, 0x3d800000, v74
	s_waitcnt lgkmcnt(4)
	v_mul_f32_e32 v138, v70, v107
	v_mul_f32_e32 v141, v70, v123
	v_fmac_f32_e32 v138, v67, v106
	v_fmac_f32_e32 v141, v67, v122
	v_fmac_f32_e32 v138, v68, v108
	v_fmac_f32_e32 v141, v68, v124
	v_fmac_f32_e32 v138, v69, v109
	v_fmac_f32_e32 v141, v69, v125
	v_mul_f32_e32 v139, v66, v111
	v_mul_f32_e32 v142, v66, v127
	v_fmac_f32_e32 v139, v63, v110
	v_fmac_f32_e32 v142, v63, v126
	v_fmac_f32_e32 v139, v64, v112
	v_fmac_f32_e32 v142, v64, v128
	v_fmac_f32_e32 v139, v65, v113
	v_fmac_f32_e32 v142, v65, v129
	v_add_f32_e32 v138, v72, v138
	v_add_f32_e32 v141, v72, v141
	v_add_f32_e32 v138, v138, v139
	v_add_f32_e32 v141, v141, v142
	v_mul_f32_e32 v139, v62, v115
	v_mul_f32_e32 v142, v62, v131
	v_fmac_f32_e32 v139, v59, v114
	v_fmac_f32_e32 v142, v59, v130
	v_fmac_f32_e32 v139, v60, v116
	v_fmac_f32_e32 v142, v60, v132
	v_fmac_f32_e32 v139, v61, v117
	v_fmac_f32_e32 v142, v61, v133
	v_add_f32_e32 v138, v138, v139
	v_add_f32_e32 v141, v141, v142
	v_mul_f32_e32 v139, v58, v119
	v_mul_f32_e32 v142, v58, v135
	v_fmac_f32_e32 v139, v53, v118
	v_fmac_f32_e32 v142, v53, v134
	v_fmac_f32_e32 v139, v57, v120
	v_fmac_f32_e32 v142, v57, v136
	v_fmac_f32_e32 v139, v9, v121
	v_fmac_f32_e32 v142, v9, v137
	v_add_f32_e32 v138, v138, v139
	v_add_f32_e32 v141, v141, v142
	ds_read_b128 v[106:109], v8 offset:24000
	ds_read_b128 v[110:113], v8 offset:24016
	ds_read_b128 v[114:117], v8 offset:24032
	ds_read_b128 v[118:121], v8 offset:24048
	v_min_f32_e32 v140, 0, v138
	v_min_f32_e32 v143, 0, v141
	v_mul_f32_e64 v138, |v138|, s2
	v_mul_f32_e64 v141, |v141|, s2
	v_exp_f32_e32 v138, v138
	v_exp_f32_e32 v141, v141
	v_add_f32_e32 v138, 1.0, v138
	v_add_f32_e32 v141, 1.0, v141
	v_log_f32_e32 v138, v138
	v_log_f32_e32 v141, v141
	v_mul_f32_e32 v139, 0x3f317217, v138
	v_mul_f32_e32 v142, 0x3f317217, v141
	v_fma_f32 v139, v138, s3, -v139
	v_fma_f32 v142, v141, s3, -v142
	v_fmac_f32_e32 v139, 0x3377d1cf, v138
	v_fmac_f32_e32 v142, 0x3377d1cf, v141
	v_fmac_f32_e32 v139, 0x3f317217, v138
	v_fmac_f32_e32 v142, 0x3f317217, v141
	v_sub_f32_e32 v138, v140, v139
	v_sub_f32_e32 v141, v143, v142
	v_fmamk_f32 v76, v138, 0x3d800000, v75
	v_fmamk_f32 v77, v141, 0x3d800000, v76
	s_waitcnt lgkmcnt(0)
	v_mul_f32_e32 v138, v70, v91
	v_mul_f32_e32 v141, v70, v107
	v_fmac_f32_e32 v138, v67, v90
	v_fmac_f32_e32 v141, v67, v106
	v_fmac_f32_e32 v138, v68, v92
	v_fmac_f32_e32 v141, v68, v108
	v_fmac_f32_e32 v138, v69, v93
	v_fmac_f32_e32 v141, v69, v109
	v_mul_f32_e32 v139, v66, v95
	v_mul_f32_e32 v142, v66, v111
	v_fmac_f32_e32 v139, v63, v94
	v_fmac_f32_e32 v142, v63, v110
	v_fmac_f32_e32 v139, v64, v96
	v_fmac_f32_e32 v142, v64, v112
	v_fmac_f32_e32 v139, v65, v97
	v_fmac_f32_e32 v142, v65, v113
	v_add_f32_e32 v138, v72, v138
	v_add_f32_e32 v141, v72, v141
	v_add_f32_e32 v138, v138, v139
	v_add_f32_e32 v141, v141, v142
	v_mul_f32_e32 v139, v62, v99
	v_mul_f32_e32 v142, v62, v115
	v_fmac_f32_e32 v139, v59, v98
	v_fmac_f32_e32 v142, v59, v114
	v_fmac_f32_e32 v139, v60, v100
	v_fmac_f32_e32 v142, v60, v116
	v_fmac_f32_e32 v139, v61, v101
	v_fmac_f32_e32 v142, v61, v117
	v_add_f32_e32 v138, v138, v139
	v_add_f32_e32 v141, v141, v142
	v_mul_f32_e32 v139, v58, v103
	v_mul_f32_e32 v142, v58, v119
	v_fmac_f32_e32 v139, v53, v102
	v_fmac_f32_e32 v142, v53, v118
	v_fmac_f32_e32 v139, v57, v104
	v_fmac_f32_e32 v142, v57, v120
	v_fmac_f32_e32 v139, v9, v105
	v_fmac_f32_e32 v142, v9, v121
	v_add_f32_e32 v138, v138, v139
	v_add_f32_e32 v141, v141, v142
	v_min_f32_e32 v140, 0, v138
	v_min_f32_e32 v143, 0, v141
	v_mul_f32_e64 v138, |v138|, s2
	v_mul_f32_e64 v141, |v141|, s2
	v_exp_f32_e32 v138, v138
	v_exp_f32_e32 v141, v141
	v_add_f32_e32 v138, 1.0, v138
	v_add_f32_e32 v141, 1.0, v141
	v_log_f32_e32 v138, v138
	v_log_f32_e32 v141, v141
	v_mul_f32_e32 v139, 0x3f317217, v138
	v_mul_f32_e32 v142, 0x3f317217, v141
	v_fma_f32 v139, v138, s3, -v139
	v_fma_f32 v142, v141, s3, -v142
	v_fmac_f32_e32 v139, 0x3377d1cf, v138
	v_fmac_f32_e32 v142, 0x3377d1cf, v141
	v_fmac_f32_e32 v139, 0x3f317217, v138
	v_fmac_f32_e32 v142, 0x3f317217, v141
	v_sub_f32_e32 v138, v140, v139
	v_sub_f32_e32 v141, v143, v142
	v_fmamk_f32 v78, v138, 0x3d800000, v77
	v_fmamk_f32 v9, v141, 0x3d800000, v78
	ds_write_b32 v11, v9 offset:25600
	ds_write_b16 v51, v0 offset:13312
	ds_write_b16_d16_hi v51, v0 offset:13392
	v_lshl_add_u32 v0, v50, 1, v52
	ds_write_b16 v0, v4 offset:13312
	ds_write_b16_d16_hi v0, v4 offset:13392
	ds_write_b16 v51, v1 offset:13472
	ds_write_b16_d16_hi v51, v1 offset:13552
	ds_write_b16 v0, v5 offset:13472
	ds_write_b16_d16_hi v0, v5 offset:13552
	ds_write_b16 v51, v2 offset:13632
	ds_write_b16_d16_hi v51, v2 offset:13712
	ds_write_b16 v0, v6 offset:13632
	ds_write_b16_d16_hi v0, v6 offset:13712
	ds_write_b16 v51, v3 offset:13792
	ds_write_b16_d16_hi v51, v3 offset:13872
	ds_write_b16 v0, v7 offset:13792
	ds_write_b16_d16_hi v0, v7 offset:13872
	v_cmp_lt_i32_e32 vcc, 0, v55
	v_mov_b32_e32 v2, 0
	s_waitcnt lgkmcnt(0)
	s_barrier
	s_and_saveexec_b64 s[0:1], vcc
	s_cbranch_execz .LBB0_322
	ds_read_b32 v0, v152 offset:25600
	s_waitcnt lgkmcnt(0)
	v_add_f32_e32 v2, 0, v0
	s_or_b64 exec, exec, s[0:1]
	v_cmp_lt_i32_e32 vcc, 1, v55
	s_and_saveexec_b64 s[0:1], vcc
	s_cbranch_execnz .LBB0_323

.LBB0_193:
	s_or_b64 exec, exec, s[0:1]
	v_add_f32_e32 v5, v71, v2
	v_mul_f32_e32 v5, 0x3fb8aa3b, v5
	v_lshlrev_b32_e32 v0, 3, v12
	v_lshlrev_b32_e32 v1, 1, v10
	v_exp_f32_e64 v144, -v5
	v_exp_f32_e32 v5, v5
	v_add3_u32 v52, v13, v1, v0
	v_ashrrev_i32_e32 v53, 31, v52
	v_readlane_b32 s0, v249, 49
	v_lshlrev_b32_e32 v4, 16, v31
	v_lshlrev_b64 v[0:1], 12, v[52:53]
	v_readlane_b32 s1, v249, 50
	v_lshlrev_b32_e32 v31, 16, v37
	v_lshlrev_b32_e32 v37, 16, v41
	v_lshl_add_u64 v[0:1], s[0:1], 0, v[0:1]
	v_lshlrev_b32_e32 v41, 16, v45
	v_lshlrev_b32_e32 v6, 16, v34
	v_lshlrev_b32_e32 v34, 16, v38
	v_lshlrev_b32_e32 v38, 16, v42
	v_lshlrev_b32_e32 v42, 16, v46
	v_lshlrev_b32_e32 v7, 16, v35
	v_lshlrev_b32_e32 v35, 16, v39
	v_lshlrev_b32_e32 v39, 16, v43
	v_lshlrev_b32_e32 v43, 16, v47
	v_lshlrev_b32_e32 v50, 5, v55
	v_lshlrev_b32_e32 v3, 16, v30
	v_and_b32_e32 v10, 7, v33
	v_mul_f32_e32 v4, v4, v144
	v_bitop3_b32 v12, v50, 56, v33 bitop3:0x48
	v_mul_f32_e32 v3, v5, v3
	v_or3_b32 v5, v12, v8, v10
	v_lshlrev_b32_e32 v30, 16, v36
	v_lshlrev_b32_e32 v36, 16, v40
	v_lshlrev_b32_e32 v40, 16, v44
	v_mul_u32_u24_e32 v44, 40, v54
	v_cvt_pk_bf16_f32 v3, v3, s0
	v_lshlrev_b32_e32 v5, 1, v5
	v_cvt_pk_bf16_f32 v4, v4, s0
	ds_write_b16 v5, v3
	ds_write_b16 v5, v4 offset:4096
	v_lshlrev_b32_e32 v5, 1, v44
	v_lshl_add_u32 v8, v28, 1, v5
	v_add_f32_e32 v5, v73, v2
	v_mul_f32_e32 v5, 0x3fb8aa3b, v5
	v_exp_f32_e64 v145, -v5
	v_exp_f32_e32 v13, v5
	ds_write_b16 v8, v4 offset:8192
	v_lshl_or_b32 v4, v29, 6, v54
	v_ashrrev_i32_e32 v5, 31, v4
	v_lshl_add_u64 v[4:5], v[4:5], 1, v[0:1]
	global_store_short v[4:5], v3, off
	v_mul_f32_e32 v3, v13, v6
	v_lshlrev_b32_e32 v5, 6, v27
	v_or3_b32 v5, v12, v5, v10
	v_cvt_pk_bf16_f32 v3, v3, s0
	v_mul_f32_e32 v4, v7, v145
	v_lshlrev_b32_e32 v5, 1, v5
	v_cvt_pk_bf16_f32 v4, v4, s0
	ds_write_b16 v5, v3
	ds_write_b16 v5, v4 offset:4096
	ds_write_b16 v8, v4 offset:8194
	v_add_f32_e32 v5, v74, v2
	v_mul_f32_e32 v5, 0x3fb8aa3b, v5
	v_exp_f32_e64 v146, -v5
	v_exp_f32_e32 v6, v5
	v_lshl_or_b32 v4, v26, 6, v54
	v_ashrrev_i32_e32 v5, 31, v4
	v_lshl_add_u64 v[4:5], v[4:5], 1, v[0:1]
	global_store_short v[4:5], v3, off
	v_mul_f32_e32 v3, v6, v30
	v_cvt_pk_bf16_f32 v3, v3, s0
	v_mul_f32_e32 v4, v31, v146
	v_lshlrev_b32_e32 v6, 2, v25
	v_lshlrev_b32_e32 v5, 6, v25
	v_bitop3_b32 v6, v6, 56, v33 bitop3:0x48
	v_or3_b32 v5, v6, v5, v10
	v_lshlrev_b32_e32 v5, 1, v5
	v_cvt_pk_bf16_f32 v4, v4, s0
	ds_write_b16 v5, v3
	ds_write_b16 v5, v4 offset:4096
	ds_write_b16 v8, v4 offset:8196
	v_add_f32_e32 v5, v75, v2
	v_mul_f32_e32 v5, 0x3fb8aa3b, v5
	v_exp_f32_e64 v147, -v5
	v_exp_f32_e32 v6, v5
	v_lshl_or_b32 v4, v24, 6, v54
	v_ashrrev_i32_e32 v5, 31, v4
	v_lshl_add_u64 v[4:5], v[4:5], 1, v[0:1]
	global_store_short v[4:5], v3, off
	v_mul_f32_e32 v3, v6, v34
	v_cvt_pk_bf16_f32 v3, v3, s0
	v_mul_f32_e32 v4, v35, v147
	v_lshlrev_b32_e32 v6, 2, v23
	v_lshlrev_b32_e32 v5, 6, v23
	v_bitop3_b32 v6, v6, 56, v33 bitop3:0x48
	v_or3_b32 v5, v6, v5, v10
	v_lshlrev_b32_e32 v5, 1, v5
	v_cvt_pk_bf16_f32 v4, v4, s0
	ds_write_b16 v5, v3
	ds_write_b16 v5, v4 offset:4096
	ds_write_b16 v8, v4 offset:8198
	v_add_f32_e32 v5, v76, v2
	v_mul_f32_e32 v5, 0x3fb8aa3b, v5
	v_exp_f32_e64 v148, -v5
	v_exp_f32_e32 v6, v5
	v_lshl_or_b32 v4, v22, 6, v54
	v_ashrrev_i32_e32 v5, 31, v4
	v_lshl_add_u64 v[4:5], v[4:5], 1, v[0:1]
	global_store_short v[4:5], v3, off
	v_mul_f32_e32 v3, v6, v36
	v_cvt_pk_bf16_f32 v3, v3, s0
	v_mul_f32_e32 v4, v37, v148
	v_lshlrev_b32_e32 v6, 2, v21
	v_lshlrev_b32_e32 v5, 6, v21
	v_bitop3_b32 v6, v6, 56, v33 bitop3:0x48
	v_or3_b32 v5, v6, v5, v10
	v_lshlrev_b32_e32 v5, 1, v5
	v_cvt_pk_bf16_f32 v4, v4, s0
	ds_write_b16 v5, v3
	ds_write_b16 v5, v4 offset:4096
	ds_write_b16 v8, v4 offset:8200
	v_add_f32_e32 v5, v77, v2
	v_mul_f32_e32 v5, 0x3fb8aa3b, v5
	v_exp_f32_e64 v149, -v5
	v_exp_f32_e32 v6, v5
	v_lshl_or_b32 v4, v20, 6, v54
	v_ashrrev_i32_e32 v5, 31, v4
	v_lshl_add_u64 v[4:5], v[4:5], 1, v[0:1]
	global_store_short v[4:5], v3, off
	v_mul_f32_e32 v3, v6, v38
	v_cvt_pk_bf16_f32 v3, v3, s0
	v_mul_f32_e32 v4, v39, v149
	v_lshlrev_b32_e32 v6, 2, v19
	v_lshlrev_b32_e32 v5, 6, v19
	v_bitop3_b32 v6, v6, 56, v33 bitop3:0x48
	v_or3_b32 v5, v6, v5, v10
	v_lshlrev_b32_e32 v5, 1, v5
	v_cvt_pk_bf16_f32 v4, v4, s0
	ds_write_b16 v5, v3
	ds_write_b16 v5, v4 offset:4096
	ds_write_b16 v8, v4 offset:8202
	v_add_f32_e32 v5, v78, v2
	v_mul_f32_e32 v5, 0x3fb8aa3b, v5
	v_exp_f32_e64 v150, -v5
	v_exp_f32_e32 v6, v5
	v_lshl_or_b32 v4, v18, 6, v54
	v_ashrrev_i32_e32 v5, 31, v4
	v_lshl_add_u64 v[4:5], v[4:5], 1, v[0:1]
	global_store_short v[4:5], v3, off
	v_mul_f32_e32 v3, v6, v40
	v_cvt_pk_bf16_f32 v13, v3, s0
	v_lshlrev_b32_e32 v5, 2, v17
	v_add_f32_e32 v2, v9, v2
	v_lshlrev_b32_e32 v4, 6, v17
	v_bitop3_b32 v5, v5, 56, v33 bitop3:0x48
	v_mul_f32_e32 v2, 0x3fb8aa3b, v2
	v_mul_f32_e32 v3, v41, v150
	v_or3_b32 v4, v5, v4, v10
	v_exp_f32_e64 v151, -v2
	v_exp_f32_e32 v6, v2
	v_lshlrev_b32_e32 v4, 1, v4
	v_cvt_pk_bf16_f32 v3, v3, s0
	ds_write_b16 v4, v13
	ds_write_b16 v4, v3 offset:4096
	ds_write_b16 v8, v3 offset:8204
	v_lshl_or_b32 v4, v16, 6, v54
	v_ashrrev_i32_e32 v5, 31, v4
	v_lshl_add_u64 v[2:3], v[4:5], 1, v[0:1]
	global_store_short v[2:3], v13, off
	v_mul_f32_e32 v2, v6, v42
	v_cvt_pk_bf16_f32 v7, v2, s0
	v_lshlrev_b32_e32 v4, 2, v15
	v_lshlrev_b32_e32 v3, 6, v15
	v_bitop3_b32 v4, v4, 56, v33 bitop3:0x48
	v_mul_f32_e32 v2, v43, v151
	v_or3_b32 v3, v4, v3, v10
	v_cvt_pk_bf16_f32 v2, v2, s0
	v_lshlrev_b32_e32 v3, 1, v3
	ds_write_b16 v3, v7
	ds_write_b16 v3, v2 offset:4096
	ds_write_b16 v8, v2 offset:8206
	v_lshl_or_b32 v2, v14, 6, v54
	v_ashrrev_i32_e32 v3, 31, v2
	v_lshl_add_u64 v[0:1], v[2:3], 1, v[0:1]
	v_cmp_gt_u32_e32 vcc, 64, v33
	global_store_short v[0:1], v7, off
	s_and_saveexec_b64 s[0:1], vcc
	s_cbranch_execz .LBB0_195
	ds_read_b32 v2, v152 offset:25600
	ds_read2st64_b32 v[0:1], v11 offset0:101 offset1:102
	ds_read_b32 v3, v11 offset:26368
	v_readlane_b32 s2, v249, 57
	v_readlane_b32 s3, v249, 58
	s_waitcnt lgkmcnt(1)
	v_add_f32_e32 v0, v2, v0
	v_add_f32_e32 v0, v0, v1
	s_waitcnt lgkmcnt(0)
	v_add_f32_e32 v0, v0, v3
	v_mul_f32_e32 v0, 0x3fb8aa3b, v0
	v_exp_f32_e32 v2, v0
	v_lshlrev_b64 v[0:1], 8, v[52:53]
	v_lshl_add_u64 v[0:1], s[2:3], 0, v[0:1]
	v_lshl_add_u64 v[0:1], v[0:1], 0, v[152:153]
	global_store_dword v[0:1], v2, off
